# P4: rg_carry_scan moved after the chain loop of the 128 latent-chain workgroups (32 lanes each), off the critical path
# speedup vs baseline: 1.0071x; 1.0071x over previous
.LBB0_554:
	s_branch .LBB0_560
	s_waitcnt vmcnt(0)
	v_add_u32_e32 v2, 0xfffffef0, v0
	s_movk_i32 s0, 0xffef
	v_cmp_lt_u32_e32 vcc, s0, v2
	s_and_saveexec_b64 s[0:1], vcc
	s_cbranch_execz .LBB0_559
	v_lshl_add_u32 v2, s66, 4, v0
	s_movk_i32 s2, 0x1100
	v_cmp_gt_i32_e32 vcc, s2, v2
	s_and_b64 exec, exec, vcc
	s_cbranch_execz .LBB0_559
	v_readlane_b32 s2, v250, 0
	v_readlane_b32 s3, v250, 1
	v_add_u32_e32 v2, 0xffffff00, v2
	s_load_dwordx2 s[2:3], s[2:3], 0x18
	v_bfe_u32 v9, v2, 10, 1
	v_ashrrev_i32_e32 v8, 11, v2
	v_and_b32_e32 v6, 0x3ff, v2
	v_lshlrev_b32_e32 v4, 13, v9
	v_mov_b32_e32 v5, 0
	v_lshl_add_u64 v[2:3], s[74:75], 0, v[4:5]
	v_lshlrev_b32_e32 v4, 2, v6
	v_lshl_or_b32 v6, v8, 1, v9
	v_ashrrev_i32_e32 v7, 31, v6
	v_lshlrev_b64 v[6:7], 12, v[6:7]
	s_waitcnt lgkmcnt(0)
	v_lshl_add_u64 v[6:7], s[2:3], 0, v[6:7]
	v_lshl_add_u64 v[6:7], v[6:7], 0, v[4:5]
	global_load_dword v10, v[6:7], off
	v_lshlrev_b32_e32 v6, 12, v9
	v_mov_b32_e32 v7, v5
	v_lshl_add_u64 v[2:3], v[2:3], 0, v[4:5]
	s_mov_b64 s[2:3], 0x4b4000
	v_lshl_add_u64 v[6:7], s[74:75], 0, v[6:7]
	v_lshlrev_b32_e32 v11, 6, v8
	v_lshl_add_u64 v[2:3], v[2:3], 0, s[2:3]
	v_lshl_add_u64 v[4:5], v[6:7], 0, v[4:5]
	s_mov_b64 s[2:3], 0xf9c4000
	v_add_u32_e32 v8, 0x80, v11
	v_lshl_add_u64 v[4:5], v[4:5], 0, s[2:3]
	s_mov_b32 s8, 0
	v_cmp_eq_u32_e64 s[4:5], 0, v9
	v_add_u32_e32 v9, 0xbf, v11
	s_mov_b64 s[2:3], -1
	s_mov_b32 s9, 0

.Lp4n_exit:
	v_readlane_b32 s10, v250, 0
	v_readlane_b32 s11, v250, 1
	s_load_dwordx2 s[64:65], s[10:11], 0xc8
	s_mov_b32 s66, s96
	s_cmpk_lt_u32 s66, 0x80
	s_cbranch_scc0 .Lp4scan_done
	s_waitcnt vmcnt(0)
	v_add_u32_e32 v2, 0xfffffee0, v0
	s_movk_i32 s0, 0xffdf
	v_cmp_lt_u32_e32 vcc, s0, v2
	s_and_saveexec_b64 s[0:1], vcc
	s_cbranch_execz .Lp4scan_559
	v_lshl_add_u32 v2, s66, 5, v0
	s_movk_i32 s2, 0x1100
	v_cmp_gt_i32_e32 vcc, s2, v2
	s_and_b64 exec, exec, vcc
	s_cbranch_execz .Lp4scan_559
	v_readlane_b32 s2, v250, 0
	v_readlane_b32 s3, v250, 1
	v_add_u32_e32 v2, 0xffffff00, v2
	s_load_dwordx2 s[2:3], s[2:3], 0x18
	v_bfe_u32 v9, v2, 10, 1
	v_ashrrev_i32_e32 v8, 11, v2
	v_and_b32_e32 v6, 0x3ff, v2
	v_lshlrev_b32_e32 v4, 13, v9
	v_mov_b32_e32 v5, 0
	v_lshl_add_u64 v[2:3], s[74:75], 0, v[4:5]
	v_lshlrev_b32_e32 v4, 2, v6
	v_lshl_or_b32 v6, v8, 1, v9
	v_ashrrev_i32_e32 v7, 31, v6
	v_lshlrev_b64 v[6:7], 12, v[6:7]
	s_waitcnt lgkmcnt(0)
	v_lshl_add_u64 v[6:7], s[2:3], 0, v[6:7]
	v_lshl_add_u64 v[6:7], v[6:7], 0, v[4:5]
	global_load_dword v10, v[6:7], off
	v_lshlrev_b32_e32 v6, 12, v9
	v_mov_b32_e32 v7, v5
	v_lshl_add_u64 v[2:3], v[2:3], 0, v[4:5]
	s_mov_b64 s[2:3], 0x4b4000
	v_lshl_add_u64 v[6:7], s[74:75], 0, v[6:7]
	v_lshlrev_b32_e32 v11, 6, v8
	v_lshl_add_u64 v[2:3], v[2:3], 0, s[2:3]
	v_lshl_add_u64 v[4:5], v[6:7], 0, v[4:5]
	s_mov_b64 s[2:3], 0xf9c4000
	v_add_u32_e32 v8, 0x80, v11
	v_lshl_add_u64 v[4:5], v[4:5], 0, s[2:3]
	s_mov_b32 s8, 0
	v_cmp_eq_u32_e64 s[4:5], 0, v9
	v_add_u32_e32 v9, 0xbf, v11
	s_mov_b64 s[2:3], -1
	s_mov_b32 s9, 0

.Lp4scan_559:
	s_or_b64 exec, exec, s[0:1]
.Lp4scan_done:
	s_branch .LBB0_736
.LBB0_731:
	s_mov_b32 s2, s66
